# SwiGLU GEMM epilogue hand-scheduled: packed f32 ops, scale folded into the sigmoid reciprocal, no hazard nops, saddr stores
# speedup vs baseline: 1.0133x; 1.0120x over previous
; #define LAS __attribute__((address_space(3)))
; __device__ __forceinline__ unsigned pack2(float lo, float hi) { const f32x2_t v = {lo, hi}; const bf16x2_t b = __builtin_convertvector(v, bf16x2_t); return __builtin_bit_cast(unsigned, b); }
; __device__ __forceinline__ float silu_f(float x) { return x * fast_sigmoid(x); }
; template <class Epi>
; __device__ __forceinline__ void gemm_phase(LAS unsigned char* lds, const Gemm g, const Epi& E) {
;     ...
;         E(acc, cur, wr, wc, fr, fq, rstab + (cur.pm == tag1 ? 256 : cur.pm == tag2 ? 512 : cur.pm == tag3 ? 768 : 0));
;     __device__ __forceinline__ void operator()(AccRef acc, const Unit& u, int wr, int wc, int fr, int fq, const LAS float* rsl) const {
;         const int row0 = u.pm * 256 + wr * 64 + fr, col0 = u.pn * 128 + wc * 32 + 8 * fq;
; #pragma unroll
;         for (int ai = 0; ai < 2; ++ai)
; #pragma unroll
;             for (int m = 0; m < 4; ++m) { bf16_t* rowp = O + (size_t)(row0 + ai * 128 + m * 16) * 2816 + col0; uint4 w; const float rs = rsl[ai * 128 + wr * 64 + m * 16 + fr];
;                 { const f32x4 gt = rs * acc[ai][0][m][0], up = rs * acc[ai][1][m][0]; w.x = pack2(silu_f(gt[0]) * up[0], silu_f(gt[1]) * up[1]); w.y = pack2(silu_f(gt[2]) * up[2], silu_f(gt[3]) * up[3]); }
;                 { const f32x4 gt = rs * acc[ai][0][m][1], up = rs * acc[ai][1][m][1]; w.z = pack2(silu_f(gt[0]) * up[0], silu_f(gt[1]) * up[1]); w.w = pack2(silu_f(gt[2]) * up[2], silu_f(gt[3]) * up[3]); }
;                 *(uint4*)rowp = w; }
.LBB0_611:
	s_cmp_eq_u32 s30, s48
	s_cselect_b32 s21, 0x300, 0
	s_cmp_lg_u32 s30, s47
	s_cselect_b32 s21, s21, 0x200
	s_cmp_lg_u32 s30, s46
	s_cselect_b32 s21, s21, 0x100
	v_lshl_add_u32 v150, s21, 2, v146
	ds_read2_b32 v[154:155], v150 offset1:16
	ds_read2_b32 v[156:157], v150 offset0:32 offset1:48
	ds_read2_b32 v[158:159], v150 offset0:128 offset1:144
	ds_read2_b32 v[160:161], v150 offset0:160 offset1:176
	v_lshl_add_u32 v149, s30, 8, v144
	v_lshl_or_b32 v142, s34, 7, v147
	v_lshlrev_b32_e32 v142, 1, v142
	v_mad_u32_u24 v170, v149, s97, v142
	s_waitcnt lgkmcnt(0)
	v_mul_f32_e32 v172, 0xbfb8aa3b, v154
	v_mul_f32_e32 v173, 0xbfb8aa3b, v155
	v_mul_f32_e32 v174, 0xbfb8aa3b, v156
	v_mul_f32_e32 v175, 0xbfb8aa3b, v157
	v_mul_f32_e32 v176, 0xbfb8aa3b, v158
	v_mul_f32_e32 v177, 0xbfb8aa3b, v159
	v_mul_f32_e32 v178, 0xbfb8aa3b, v160
	v_mul_f32_e32 v179, 0xbfb8aa3b, v161
	v_mul_f32_e32 v154, v154, v154
	v_mul_f32_e32 v155, v155, v155
	v_mul_f32_e32 v156, v156, v156
	v_mul_f32_e32 v157, v157, v157
	v_mul_f32_e32 v158, v158, v158
	v_mul_f32_e32 v159, v159, v159
	v_mul_f32_e32 v160, v160, v160
	v_mul_f32_e32 v161, v161, v161
	v_rcp_f32_e32 v154, v154
	v_rcp_f32_e32 v155, v155
	v_rcp_f32_e32 v156, v156
	v_rcp_f32_e32 v157, v157
	v_rcp_f32_e32 v158, v158
	v_rcp_f32_e32 v159, v159
	v_rcp_f32_e32 v160, v160
	v_rcp_f32_e32 v161, v161
	v_mov_b32_e32 v162, v172
	v_mov_b32_e32 v164, v154
	v_pk_mul_f32 v[166:167], v[124:125], v[162:163] op_sel_hi:[1,0]
	v_pk_mul_f32 v[168:169], v[126:127], v[162:163] op_sel_hi:[1,0]
	v_exp_f32_e32 v166, v166
	v_exp_f32_e32 v167, v167
	v_exp_f32_e32 v168, v168
	v_exp_f32_e32 v169, v169
	v_pk_mul_f32 v[120:121], v[124:125], v[120:121]
	v_pk_mul_f32 v[122:123], v[126:127], v[122:123]
	v_pk_fma_f32 v[166:167], v[166:167], v[164:165], v[164:165] op_sel_hi:[1,0,0]
	v_pk_fma_f32 v[168:169], v[168:169], v[164:165], v[164:165] op_sel_hi:[1,0,0]
	v_rcp_f32_e32 v166, v166
	v_rcp_f32_e32 v167, v167
	v_rcp_f32_e32 v168, v168
	v_rcp_f32_e32 v169, v169
	v_pk_mul_f32 v[120:121], v[120:121], v[166:167]
	v_pk_mul_f32 v[122:123], v[122:123], v[168:169]
	v_cvt_pk_bf16_f32 v120, v120, v121
	v_cvt_pk_bf16_f32 v121, v122, v123
	v_pk_mul_f32 v[166:167], v[116:117], v[162:163] op_sel_hi:[1,0]
	v_pk_mul_f32 v[168:169], v[118:119], v[162:163] op_sel_hi:[1,0]
	v_exp_f32_e32 v166, v166
	v_exp_f32_e32 v167, v167
	v_exp_f32_e32 v168, v168
	v_exp_f32_e32 v169, v169
	v_pk_mul_f32 v[112:113], v[116:117], v[112:113]
	v_pk_mul_f32 v[114:115], v[118:119], v[114:115]
	v_pk_fma_f32 v[166:167], v[166:167], v[164:165], v[164:165] op_sel_hi:[1,0,0]
	v_pk_fma_f32 v[168:169], v[168:169], v[164:165], v[164:165] op_sel_hi:[1,0,0]
	v_rcp_f32_e32 v166, v166
	v_rcp_f32_e32 v167, v167
	v_rcp_f32_e32 v168, v168
	v_rcp_f32_e32 v169, v169
	v_pk_mul_f32 v[112:113], v[112:113], v[166:167]
	v_pk_mul_f32 v[114:115], v[114:115], v[168:169]
	v_cvt_pk_bf16_f32 v122, v112, v113
	v_cvt_pk_bf16_f32 v123, v114, v115
	global_store_dwordx4 v170, v[120:123], s[14:15]
	v_mov_b32_e32 v162, v173
	v_mov_b32_e32 v164, v155
	v_add_u32_e32 v171, 0x16000, v170
	v_pk_mul_f32 v[166:167], v[108:109], v[162:163] op_sel_hi:[1,0]
	v_pk_mul_f32 v[168:169], v[110:111], v[162:163] op_sel_hi:[1,0]
	v_exp_f32_e32 v166, v166
	v_exp_f32_e32 v167, v167
	v_exp_f32_e32 v168, v168
	v_exp_f32_e32 v169, v169
	v_pk_mul_f32 v[104:105], v[108:109], v[104:105]
	v_pk_mul_f32 v[106:107], v[110:111], v[106:107]
	v_pk_fma_f32 v[166:167], v[166:167], v[164:165], v[164:165] op_sel_hi:[1,0,0]
	v_pk_fma_f32 v[168:169], v[168:169], v[164:165], v[164:165] op_sel_hi:[1,0,0]
	v_rcp_f32_e32 v166, v166
	v_rcp_f32_e32 v167, v167
	v_rcp_f32_e32 v168, v168
	v_rcp_f32_e32 v169, v169
	v_pk_mul_f32 v[104:105], v[104:105], v[166:167]
	v_pk_mul_f32 v[106:107], v[106:107], v[168:169]
	v_cvt_pk_bf16_f32 v104, v104, v105
	v_cvt_pk_bf16_f32 v105, v106, v107
	v_pk_mul_f32 v[166:167], v[100:101], v[162:163] op_sel_hi:[1,0]
	v_pk_mul_f32 v[168:169], v[102:103], v[162:163] op_sel_hi:[1,0]
	v_exp_f32_e32 v166, v166
	v_exp_f32_e32 v167, v167
	v_exp_f32_e32 v168, v168
	v_exp_f32_e32 v169, v169
	v_pk_mul_f32 v[96:97], v[100:101], v[96:97]
	v_pk_mul_f32 v[98:99], v[102:103], v[98:99]
	v_pk_fma_f32 v[166:167], v[166:167], v[164:165], v[164:165] op_sel_hi:[1,0,0]
	v_pk_fma_f32 v[168:169], v[168:169], v[164:165], v[164:165] op_sel_hi:[1,0,0]
	v_rcp_f32_e32 v166, v166
	v_rcp_f32_e32 v167, v167
	v_rcp_f32_e32 v168, v168
	v_rcp_f32_e32 v169, v169
	v_pk_mul_f32 v[96:97], v[96:97], v[166:167]
	v_pk_mul_f32 v[98:99], v[98:99], v[168:169]
	v_cvt_pk_bf16_f32 v106, v96, v97
	v_cvt_pk_bf16_f32 v107, v98, v99
	global_store_dwordx4 v171, v[104:107], s[14:15]
	v_mov_b32_e32 v162, v174
	v_mov_b32_e32 v164, v156
	v_add_u32_e32 v171, 0x2c000, v170
	v_pk_mul_f32 v[166:167], v[92:93], v[162:163] op_sel_hi:[1,0]
	v_pk_mul_f32 v[168:169], v[94:95], v[162:163] op_sel_hi:[1,0]
	v_exp_f32_e32 v166, v166
	v_exp_f32_e32 v167, v167
	v_exp_f32_e32 v168, v168
	v_exp_f32_e32 v169, v169
	v_pk_mul_f32 v[88:89], v[92:93], v[88:89]
	v_pk_mul_f32 v[90:91], v[94:95], v[90:91]
	v_pk_fma_f32 v[166:167], v[166:167], v[164:165], v[164:165] op_sel_hi:[1,0,0]
	v_pk_fma_f32 v[168:169], v[168:169], v[164:165], v[164:165] op_sel_hi:[1,0,0]
	v_rcp_f32_e32 v166, v166
	v_rcp_f32_e32 v167, v167
	v_rcp_f32_e32 v168, v168
	v_rcp_f32_e32 v169, v169
	v_pk_mul_f32 v[88:89], v[88:89], v[166:167]
	v_pk_mul_f32 v[90:91], v[90:91], v[168:169]
	v_cvt_pk_bf16_f32 v88, v88, v89
	v_cvt_pk_bf16_f32 v89, v90, v91
	v_pk_mul_f32 v[166:167], v[84:85], v[162:163] op_sel_hi:[1,0]
	v_pk_mul_f32 v[168:169], v[86:87], v[162:163] op_sel_hi:[1,0]
	v_exp_f32_e32 v166, v166
	v_exp_f32_e32 v167, v167
	v_exp_f32_e32 v168, v168
; __device__ __forceinline__ unsigned pack2(float lo, float hi) { const f32x2_t v = {lo, hi}; const bf16x2_t b = __builtin_convertvector(v, bf16x2_t); return __builtin_bit_cast(unsigned, b); }
; __device__ __forceinline__ float silu_f(float x) { return x * fast_sigmoid(x); }
;     __device__ __forceinline__ void operator()(AccRef acc, const Unit& u, int wr, int wc, int fr, int fq, const LAS float* rsl) const {
;     ...
;             for (int m = 0; m < 4; ++m) { bf16_t* rowp = O + (size_t)(row0 + ai * 128 + m * 16) * 2816 + col0; uint4 w; const float rs = rsl[ai * 128 + wr * 64 + m * 16 + fr];
;                 { const f32x4 gt = rs * acc[ai][0][m][0], up = rs * acc[ai][1][m][0]; w.x = pack2(silu_f(gt[0]) * up[0], silu_f(gt[1]) * up[1]); w.y = pack2(silu_f(gt[2]) * up[2], silu_f(gt[3]) * up[3]); }
;                 { const f32x4 gt = rs * acc[ai][0][m][1], up = rs * acc[ai][1][m][1]; w.z = pack2(silu_f(gt[0]) * up[0], silu_f(gt[1]) * up[1]); w.w = pack2(silu_f(gt[2]) * up[2], silu_f(gt[3]) * up[3]); }
;                 *(uint4*)rowp = w; }
	v_exp_f32_e32 v169, v169
	v_pk_mul_f32 v[80:81], v[84:85], v[80:81]
	v_pk_mul_f32 v[82:83], v[86:87], v[82:83]
	v_pk_fma_f32 v[166:167], v[166:167], v[164:165], v[164:165] op_sel_hi:[1,0,0]
	v_pk_fma_f32 v[168:169], v[168:169], v[164:165], v[164:165] op_sel_hi:[1,0,0]
	v_rcp_f32_e32 v166, v166
	v_rcp_f32_e32 v167, v167
	v_rcp_f32_e32 v168, v168
	v_rcp_f32_e32 v169, v169
	v_pk_mul_f32 v[80:81], v[80:81], v[166:167]
	v_pk_mul_f32 v[82:83], v[82:83], v[168:169]
	v_cvt_pk_bf16_f32 v90, v80, v81
	v_cvt_pk_bf16_f32 v91, v82, v83
	global_store_dwordx4 v171, v[88:91], s[14:15]
	v_mov_b32_e32 v162, v175
	v_mov_b32_e32 v164, v157
	v_add_u32_e32 v171, 0x42000, v170
	v_pk_mul_f32 v[166:167], v[76:77], v[162:163] op_sel_hi:[1,0]
	v_pk_mul_f32 v[168:169], v[78:79], v[162:163] op_sel_hi:[1,0]
	v_exp_f32_e32 v166, v166
	v_exp_f32_e32 v167, v167
	v_exp_f32_e32 v168, v168
	v_exp_f32_e32 v169, v169
	v_pk_mul_f32 v[72:73], v[76:77], v[72:73]
	v_pk_mul_f32 v[74:75], v[78:79], v[74:75]
	v_pk_fma_f32 v[166:167], v[166:167], v[164:165], v[164:165] op_sel_hi:[1,0,0]
	v_pk_fma_f32 v[168:169], v[168:169], v[164:165], v[164:165] op_sel_hi:[1,0,0]
	v_rcp_f32_e32 v166, v166
	v_rcp_f32_e32 v167, v167
	v_rcp_f32_e32 v168, v168
	v_rcp_f32_e32 v169, v169
	v_pk_mul_f32 v[72:73], v[72:73], v[166:167]
	v_pk_mul_f32 v[74:75], v[74:75], v[168:169]
	v_cvt_pk_bf16_f32 v72, v72, v73
	v_cvt_pk_bf16_f32 v73, v74, v75
	v_pk_mul_f32 v[166:167], v[68:69], v[162:163] op_sel_hi:[1,0]
	v_pk_mul_f32 v[168:169], v[70:71], v[162:163] op_sel_hi:[1,0]
	v_exp_f32_e32 v166, v166
	v_exp_f32_e32 v167, v167
	v_exp_f32_e32 v168, v168
	v_exp_f32_e32 v169, v169
	v_pk_mul_f32 v[64:65], v[68:69], v[64:65]
	v_pk_mul_f32 v[66:67], v[70:71], v[66:67]
	v_pk_fma_f32 v[166:167], v[166:167], v[164:165], v[164:165] op_sel_hi:[1,0,0]
	v_pk_fma_f32 v[168:169], v[168:169], v[164:165], v[164:165] op_sel_hi:[1,0,0]
	v_rcp_f32_e32 v166, v166
	v_rcp_f32_e32 v167, v167
	v_rcp_f32_e32 v168, v168
	v_rcp_f32_e32 v169, v169
	v_pk_mul_f32 v[64:65], v[64:65], v[166:167]
	v_pk_mul_f32 v[66:67], v[66:67], v[168:169]
	v_cvt_pk_bf16_f32 v74, v64, v65
	v_cvt_pk_bf16_f32 v75, v66, v67
	global_store_dwordx4 v171, v[72:75], s[14:15]
	v_mov_b32_e32 v162, v176
	v_mov_b32_e32 v164, v158
	v_add_u32_e32 v171, 0xb0000, v170
	v_pk_mul_f32 v[166:167], v[60:61], v[162:163] op_sel_hi:[1,0]
	v_pk_mul_f32 v[168:169], v[62:63], v[162:163] op_sel_hi:[1,0]
	v_exp_f32_e32 v166, v166
	v_exp_f32_e32 v167, v167
	v_exp_f32_e32 v168, v168
	v_exp_f32_e32 v169, v169
	v_pk_mul_f32 v[56:57], v[60:61], v[56:57]
	v_pk_mul_f32 v[58:59], v[62:63], v[58:59]
	v_pk_fma_f32 v[166:167], v[166:167], v[164:165], v[164:165] op_sel_hi:[1,0,0]
	v_pk_fma_f32 v[168:169], v[168:169], v[164:165], v[164:165] op_sel_hi:[1,0,0]
	v_rcp_f32_e32 v166, v166
	v_rcp_f32_e32 v167, v167
	v_rcp_f32_e32 v168, v168
	v_rcp_f32_e32 v169, v169
	v_pk_mul_f32 v[56:57], v[56:57], v[166:167]
	v_pk_mul_f32 v[58:59], v[58:59], v[168:169]
	v_cvt_pk_bf16_f32 v56, v56, v57
	v_cvt_pk_bf16_f32 v57, v58, v59
	v_pk_mul_f32 v[166:167], v[52:53], v[162:163] op_sel_hi:[1,0]
	v_pk_mul_f32 v[168:169], v[54:55], v[162:163] op_sel_hi:[1,0]
	v_exp_f32_e32 v166, v166
	v_exp_f32_e32 v167, v167
	v_exp_f32_e32 v168, v168
	v_exp_f32_e32 v169, v169
	v_pk_mul_f32 v[48:49], v[52:53], v[48:49]
	v_pk_mul_f32 v[50:51], v[54:55], v[50:51]
	v_pk_fma_f32 v[166:167], v[166:167], v[164:165], v[164:165] op_sel_hi:[1,0,0]
	v_pk_fma_f32 v[168:169], v[168:169], v[164:165], v[164:165] op_sel_hi:[1,0,0]
	v_rcp_f32_e32 v166, v166
	v_rcp_f32_e32 v167, v167
	v_rcp_f32_e32 v168, v168
	v_rcp_f32_e32 v169, v169
	v_pk_mul_f32 v[48:49], v[48:49], v[166:167]
	v_pk_mul_f32 v[50:51], v[50:51], v[168:169]
	v_cvt_pk_bf16_f32 v58, v48, v49
	v_cvt_pk_bf16_f32 v59, v50, v51
	global_store_dwordx4 v171, v[56:59], s[14:15]
	v_mov_b32_e32 v162, v177
	v_mov_b32_e32 v164, v159
	v_add_u32_e32 v171, 0xc6000, v170
	v_pk_mul_f32 v[166:167], v[44:45], v[162:163] op_sel_hi:[1,0]
	v_pk_mul_f32 v[168:169], v[46:47], v[162:163] op_sel_hi:[1,0]
	v_exp_f32_e32 v166, v166
	v_exp_f32_e32 v167, v167
	v_exp_f32_e32 v168, v168
	v_exp_f32_e32 v169, v169
	v_pk_mul_f32 v[40:41], v[44:45], v[40:41]
	v_pk_mul_f32 v[42:43], v[46:47], v[42:43]
	v_pk_fma_f32 v[166:167], v[166:167], v[164:165], v[164:165] op_sel_hi:[1,0,0]
	v_pk_fma_f32 v[168:169], v[168:169], v[164:165], v[164:165] op_sel_hi:[1,0,0]
	v_rcp_f32_e32 v166, v166
; __device__ __forceinline__ unsigned pack2(float lo, float hi) { const f32x2_t v = {lo, hi}; const bf16x2_t b = __builtin_convertvector(v, bf16x2_t); return __builtin_bit_cast(unsigned, b); }
; __device__ __forceinline__ float silu_f(float x) { return x * fast_sigmoid(x); }
; template <class Epi>
; __device__ __forceinline__ void gemm_phase(LAS unsigned char* lds, const Gemm g, const Epi& E) {
;     ...
;         if (!has_next) break;
;     __device__ __forceinline__ void operator()(AccRef acc, const Unit& u, int wr, int wc, int fr, int fq, const LAS float* rsl) const {
;     ...
;             for (int m = 0; m < 4; ++m) { bf16_t* rowp = O + (size_t)(row0 + ai * 128 + m * 16) * 2816 + col0; uint4 w; const float rs = rsl[ai * 128 + wr * 64 + m * 16 + fr];
;                 { const f32x4 gt = rs * acc[ai][0][m][0], up = rs * acc[ai][1][m][0]; w.x = pack2(silu_f(gt[0]) * up[0], silu_f(gt[1]) * up[1]); w.y = pack2(silu_f(gt[2]) * up[2], silu_f(gt[3]) * up[3]); }
;                 { const f32x4 gt = rs * acc[ai][0][m][1], up = rs * acc[ai][1][m][1]; w.z = pack2(silu_f(gt[0]) * up[0], silu_f(gt[1]) * up[1]); w.w = pack2(silu_f(gt[2]) * up[2], silu_f(gt[3]) * up[3]); }
;                 *(uint4*)rowp = w; }
	v_rcp_f32_e32 v167, v167
	v_rcp_f32_e32 v168, v168
	v_rcp_f32_e32 v169, v169
	v_pk_mul_f32 v[40:41], v[40:41], v[166:167]
	v_pk_mul_f32 v[42:43], v[42:43], v[168:169]
	v_cvt_pk_bf16_f32 v40, v40, v41
	v_cvt_pk_bf16_f32 v41, v42, v43
	v_pk_mul_f32 v[166:167], v[36:37], v[162:163] op_sel_hi:[1,0]
	v_pk_mul_f32 v[168:169], v[38:39], v[162:163] op_sel_hi:[1,0]
	v_exp_f32_e32 v166, v166
	v_exp_f32_e32 v167, v167
	v_exp_f32_e32 v168, v168
	v_exp_f32_e32 v169, v169
	v_pk_mul_f32 v[32:33], v[36:37], v[32:33]
	v_pk_mul_f32 v[34:35], v[38:39], v[34:35]
	v_pk_fma_f32 v[166:167], v[166:167], v[164:165], v[164:165] op_sel_hi:[1,0,0]
	v_pk_fma_f32 v[168:169], v[168:169], v[164:165], v[164:165] op_sel_hi:[1,0,0]
	v_rcp_f32_e32 v166, v166
	v_rcp_f32_e32 v167, v167
	v_rcp_f32_e32 v168, v168
	v_rcp_f32_e32 v169, v169
	v_pk_mul_f32 v[32:33], v[32:33], v[166:167]
	v_pk_mul_f32 v[34:35], v[34:35], v[168:169]
	v_cvt_pk_bf16_f32 v42, v32, v33
	v_cvt_pk_bf16_f32 v43, v34, v35
	global_store_dwordx4 v171, v[40:43], s[14:15]
	v_mov_b32_e32 v162, v178
	v_mov_b32_e32 v164, v160
	v_add_u32_e32 v171, 0xdc000, v170
	v_pk_mul_f32 v[166:167], v[28:29], v[162:163] op_sel_hi:[1,0]
	v_pk_mul_f32 v[168:169], v[30:31], v[162:163] op_sel_hi:[1,0]
	v_exp_f32_e32 v166, v166
	v_exp_f32_e32 v167, v167
	v_exp_f32_e32 v168, v168
	v_exp_f32_e32 v169, v169
	v_pk_mul_f32 v[24:25], v[28:29], v[24:25]
	v_pk_mul_f32 v[26:27], v[30:31], v[26:27]
	v_pk_fma_f32 v[166:167], v[166:167], v[164:165], v[164:165] op_sel_hi:[1,0,0]
	v_pk_fma_f32 v[168:169], v[168:169], v[164:165], v[164:165] op_sel_hi:[1,0,0]
	v_rcp_f32_e32 v166, v166
	v_rcp_f32_e32 v167, v167
	v_rcp_f32_e32 v168, v168
	v_rcp_f32_e32 v169, v169
	v_pk_mul_f32 v[24:25], v[24:25], v[166:167]
	v_pk_mul_f32 v[26:27], v[26:27], v[168:169]
	v_cvt_pk_bf16_f32 v24, v24, v25
	v_cvt_pk_bf16_f32 v25, v26, v27
	v_pk_mul_f32 v[166:167], v[20:21], v[162:163] op_sel_hi:[1,0]
	v_pk_mul_f32 v[168:169], v[22:23], v[162:163] op_sel_hi:[1,0]
	v_exp_f32_e32 v166, v166
	v_exp_f32_e32 v167, v167
	v_exp_f32_e32 v168, v168
	v_exp_f32_e32 v169, v169
	v_pk_mul_f32 v[16:17], v[20:21], v[16:17]
	v_pk_mul_f32 v[18:19], v[22:23], v[18:19]
	v_pk_fma_f32 v[166:167], v[166:167], v[164:165], v[164:165] op_sel_hi:[1,0,0]
	v_pk_fma_f32 v[168:169], v[168:169], v[164:165], v[164:165] op_sel_hi:[1,0,0]
	v_rcp_f32_e32 v166, v166
	v_rcp_f32_e32 v167, v167
	v_rcp_f32_e32 v168, v168
	v_rcp_f32_e32 v169, v169
	v_pk_mul_f32 v[16:17], v[16:17], v[166:167]
	v_pk_mul_f32 v[18:19], v[18:19], v[168:169]
	v_cvt_pk_bf16_f32 v26, v16, v17
	v_cvt_pk_bf16_f32 v27, v18, v19
	global_store_dwordx4 v171, v[24:27], s[14:15]
	v_mov_b32_e32 v162, v179
	v_mov_b32_e32 v164, v161
	v_add_u32_e32 v171, 0xf2000, v170
	v_pk_mul_f32 v[166:167], v[12:13], v[162:163] op_sel_hi:[1,0]
	v_pk_mul_f32 v[168:169], v[14:15], v[162:163] op_sel_hi:[1,0]
	v_exp_f32_e32 v166, v166
	v_exp_f32_e32 v167, v167
	v_exp_f32_e32 v168, v168
	v_exp_f32_e32 v169, v169
	v_pk_mul_f32 v[8:9], v[12:13], v[8:9]
	v_pk_mul_f32 v[10:11], v[14:15], v[10:11]
	v_pk_fma_f32 v[166:167], v[166:167], v[164:165], v[164:165] op_sel_hi:[1,0,0]
	v_pk_fma_f32 v[168:169], v[168:169], v[164:165], v[164:165] op_sel_hi:[1,0,0]
	v_rcp_f32_e32 v166, v166
	v_rcp_f32_e32 v167, v167
	v_rcp_f32_e32 v168, v168
	v_rcp_f32_e32 v169, v169
	v_pk_mul_f32 v[8:9], v[8:9], v[166:167]
	v_pk_mul_f32 v[10:11], v[10:11], v[168:169]
	v_cvt_pk_bf16_f32 v8, v8, v9
	v_cvt_pk_bf16_f32 v9, v10, v11
	v_pk_mul_f32 v[166:167], v[4:5], v[162:163] op_sel_hi:[1,0]
	v_pk_mul_f32 v[168:169], v[6:7], v[162:163] op_sel_hi:[1,0]
	v_exp_f32_e32 v166, v166
	v_exp_f32_e32 v167, v167
	v_exp_f32_e32 v168, v168
	v_exp_f32_e32 v169, v169
	v_pk_mul_f32 v[0:1], v[4:5], v[0:1]
	v_pk_mul_f32 v[2:3], v[6:7], v[2:3]
	v_pk_fma_f32 v[166:167], v[166:167], v[164:165], v[164:165] op_sel_hi:[1,0,0]
	v_pk_fma_f32 v[168:169], v[168:169], v[164:165], v[164:165] op_sel_hi:[1,0,0]
	v_rcp_f32_e32 v166, v166
	v_rcp_f32_e32 v167, v167
	v_rcp_f32_e32 v168, v168
	v_rcp_f32_e32 v169, v169
	v_pk_mul_f32 v[0:1], v[0:1], v[166:167]
	v_pk_mul_f32 v[2:3], v[2:3], v[168:169]
	v_cvt_pk_bf16_f32 v10, v0, v1
	v_cvt_pk_bf16_f32 v11, v2, v3
	global_store_dwordx4 v171, v[8:11], s[14:15]
	s_mov_b64 s[30:31], -1
	s_andn2_b64 vcc, exec, s[40:41]
	s_cbranch_vccnz .LBB0_604
	s_andn2_b64 vcc, exec, s[16:17]
	s_cbranch_vccnz .LBB0_603
	s_barrier
	s_branch .LBB0_603
